# v31 plus ret_kv tile loads issued together
# speedup vs baseline: 1.0212x; 1.0025x over previous
; #define LAS __attribute__((address_space(3)))
; __device__ __forceinline__ bf16_t f2bf(float f) { return (bf16_t)(pk_bf16(f, 0.f) & 0xffffu); }
; __device__ __forceinline__ float bflo(unsigned w) { return __uint_as_float(w << 16); }
; __device__ __forceinline__ float bfhi(unsigned w) { return __uint_as_float(w & 0xffff0000u); }
; __device__ __forceinline__ void ret_kv_unit(int b, int h, int c, LAS unsigned char* lds, const bf16_t* PROJ, float* KV, int tid) {
;     ...
;     for (int r = 0; r < 4; ++r) { const int idx = tid + 512 * r, tok = idx & 127, seg = idx >> 7;
;         const bf16_t* rp = PROJ + (R0 + tok) * EIN + h * 128 + seg * 8;
;         const u32x4 kv = *(const u32x4*)(rp + 1024), vv = *(const u32x4*)(rp + 2048);
;         const float wj = exp2f(lg2 * (float)(127 - tok)) * 0.08838834764831845f;
; #pragma unroll
;         for (int i = 0; i < 4; ++i) {
;             *(LAS bf16_t*)(KT + (seg * 8 + 2 * i) * 272 + tok * 2) = f2bf(bflo(kv[i]) * wj);
;             *(LAS bf16_t*)(KT + (seg * 8 + 2 * i + 1) * 272 + tok * 2) = f2bf(bfhi(kv[i]) * wj);
;             *(LAS bf16_t*)(VT + (seg * 8 + 2 * i) * 272 + tok * 2) = (bf16_t)(vv[i] & 0xffffu);
;             *(LAS bf16_t*)(VT + (seg * 8 + 2 * i + 1) * 272 + tok * 2) = (bf16_t)(vv[i] >> 16); } }
.LBB0_470:
	s_bfe_u32 s1, s38, 0x30005
	v_cvt_f32_ubyte0_e32 v0, s1
	v_sub_f32_e32 v0, 0xc0a00000, v0
	v_cmp_gt_f32_e32 vcc, s34, v0
	s_and_b32 s0, s38, 31
	s_and_b64 s[4:5], vcc, exec
	v_cndmask_b32_e32 v1, 0, v168, vcc
	v_add_f32_e32 v0, v0, v1
	v_exp_f32_e32 v0, v0
	s_cselect_b32 s4, 0xffffffc0, 0
	v_and_b32_e32 v5, 0x7f, v47
	s_movk_i32 s18, 0x110
	v_ldexp_f32 v0, v0, s4
	v_sub_f32_e32 v0, 1.0, v0
	v_cmp_gt_f32_e32 vcc, s43, v0
	s_and_b64 s[4:5], vcc, exec
	s_cselect_b32 s4, 32, 0
	v_ldexp_f32 v0, v0, s4
	v_log_f32_e32 v0, v0
	s_lshl_b32 s4, s38, 4
	s_and_b32 s4, s4, 0x1000
	s_lshl_b32 s5, s0, 7
	v_cndmask_b32_e32 v1, 0, v170, vcc
	s_or_b32 s4, s5, s4
	v_sub_f32_e32 v4, v0, v1
	v_or_b32_e32 v0, s4, v5
	v_mul_u32_u24_e32 v0, 0x1500, v0
	v_lshlrev_b32_e32 v128, 1, v0
	v_lshl_add_u64 v[0:1], s[14:15], 0, v[128:129]
	s_lshl_b32 s24, s1, 8
	s_movk_i32 s4, 0x7f
	v_lshl_add_u64 v[2:3], v[0:1], 0, s[24:25]
	v_bitop3_b32 v0, v47, s4, v47 bitop3:0xc
	v_cvt_f32_ubyte0_e32 v0, v0
	v_mul_f32_e32 v1, v4, v0
	v_cmp_gt_f32_e32 vcc, s34, v1
	v_and_b32_e32 v128, 48, v47
	v_and_b32_e32 v17, 15, v47
	v_cndmask_b32_e32 v1, 0, v168, vcc
	v_fmac_f32_e32 v1, v4, v0
	v_exp_f32_e32 v0, v1
	v_ashrrev_i32_e32 v4, 4, v47
	v_and_b32_e32 v12, -8, v4
	v_cndmask_b32_e32 v1, 0, v171, vcc
	v_ashrrev_i32_e32 v13, 31, v12
	v_ldexp_f32 v0, v0, v1
	v_lshl_add_u64 v[8:9], v[12:13], 1, v[2:3]
	v_mul_f32_e32 v1, 0x3db504f3, v0
	v_lshl_add_u32 v0, v5, 1, 0
	v_ashrrev_i32_e32 v244, 4, v47
	v_and_b32_e32 v244, -8, v244
	v_ashrrev_i32_e32 v245, 31, v244
	v_lshl_add_u64 v[246:247], v[244:245], 1, v[2:3]
	global_load_dwordx4 v[212:215], v[246:247], off offset:2048
	v_add_co_u32_e32 v246, vcc, s33, v246
	s_nop 1
	v_addc_co_u32_e32 v247, vcc, 0, v247, vcc
	global_load_dwordx4 v[216:219], v[246:247], off
	v_add_u32_e32 v244, 0x200, v47
	v_ashrrev_i32_e32 v244, 4, v244
	v_and_b32_e32 v244, -8, v244
	v_ashrrev_i32_e32 v245, 31, v244
	v_lshl_add_u64 v[246:247], v[244:245], 1, v[2:3]
	global_load_dwordx4 v[220:223], v[246:247], off offset:2048
	v_add_co_u32_e32 v246, vcc, s33, v246
	s_nop 1
	v_addc_co_u32_e32 v247, vcc, 0, v247, vcc
	global_load_dwordx4 v[224:227], v[246:247], off
	v_add_u32_e32 v244, 0x400, v47
	v_ashrrev_i32_e32 v244, 4, v244
	v_and_b32_e32 v244, -8, v244
	v_ashrrev_i32_e32 v245, 31, v244
	v_lshl_add_u64 v[246:247], v[244:245], 1, v[2:3]
	global_load_dwordx4 v[228:231], v[246:247], off offset:2048
	v_add_co_u32_e32 v246, vcc, s33, v246
	s_nop 1
	v_addc_co_u32_e32 v247, vcc, 0, v247, vcc
	global_load_dwordx4 v[232:235], v[246:247], off
	v_add_u32_e32 v244, 0x600, v47
	v_ashrrev_i32_e32 v244, 4, v244
	v_and_b32_e32 v244, -8, v244
	v_ashrrev_i32_e32 v245, 31, v244
	v_lshl_add_u64 v[246:247], v[244:245], 1, v[2:3]
	global_load_dwordx4 v[236:239], v[246:247], off offset:2048
	v_add_co_u32_e32 v246, vcc, s33, v246
	s_nop 1
	v_addc_co_u32_e32 v247, vcc, 0, v247, vcc
	global_load_dwordx4 v[240:243], v[246:247], off
	s_waitcnt vmcnt(0)
	v_mov_b64_e32 v[4:5], v[212:213]
	v_mov_b64_e32 v[6:7], v[214:215]
	v_add_co_u32_e32 v8, vcc, s33, v8
	s_waitcnt vmcnt(7)
	v_add_u32_e32 v20, 0, v128
	v_addc_co_u32_e32 v9, vcc, 0, v9, vcc
	v_mad_u32_u24 v17, v17, s18, v20
	s_lshl_b32 s1, s1, 5
	s_waitcnt vmcnt(0)
	v_lshlrev_b32_e32 v10, 16, v4
	v_mul_f32_e32 v13, v1, v10
	v_mov_b64_e32 v[8:9], v[216:217]
	v_mov_b64_e32 v[10:11], v[218:219]
	v_and_b32_e32 v4, 0xffff0000, v4
	v_cvt_pk_bf16_f32 v14, v13, v129
	v_mad_u64_u32 v[12:13], s[4:5], v12, s18, v[0:1]
	v_mul_f32_e32 v4, v1, v4
	ds_write_b16 v12, v14
	v_cvt_pk_bf16_f32 v4, v4, v129
	ds_write_b16 v12, v4 offset:272
	s_waitcnt vmcnt(0)
	ds_write_b16 v12, v8 offset:34816
	ds_write_b16_d16_hi v12, v8 offset:35088
	v_lshlrev_b32_e32 v4, 16, v5
	v_mul_f32_e32 v4, v1, v4
	v_cvt_pk_bf16_f32 v4, v4, v129
	ds_write_b16 v12, v4 offset:544
	v_and_b32_e32 v4, 0xffff0000, v5
	v_mul_f32_e32 v4, v1, v4
	v_cvt_pk_bf16_f32 v4, v4, v129
	ds_write_b16 v12, v4 offset:816
	ds_write_b16 v12, v9 offset:35360
	ds_write_b16_d16_hi v12, v9 offset:35632
	v_lshlrev_b32_e32 v4, 16, v6
	v_mul_f32_e32 v4, v1, v4
	v_cvt_pk_bf16_f32 v4, v4, v129
	ds_write_b16 v12, v4 offset:1088
	v_and_b32_e32 v4, 0xffff0000, v6
	v_mul_f32_e32 v4, v1, v4
	v_cvt_pk_bf16_f32 v4, v4, v129
	ds_write_b16 v12, v4 offset:1360
	ds_write_b16 v12, v10 offset:35904
	ds_write_b16_d16_hi v12, v10 offset:36176
	v_lshlrev_b32_e32 v4, 16, v7
	v_mul_f32_e32 v4, v1, v4
	v_cvt_pk_bf16_f32 v4, v4, v129
	ds_write_b16 v12, v4 offset:1632
	v_and_b32_e32 v4, 0xffff0000, v7
	v_mul_f32_e32 v4, v1, v4
	v_cvt_pk_bf16_f32 v4, v4, v129
	ds_write_b16 v12, v4 offset:1904
	ds_write_b16 v12, v11 offset:36448
	ds_write_b16_d16_hi v12, v11 offset:36720
	v_add_u32_e32 v4, 0x200, v47
	v_ashrrev_i32_e32 v4, 4, v4
	v_and_b32_e32 v12, -8, v4
	v_ashrrev_i32_e32 v13, 31, v12
	v_lshl_add_u64 v[8:9], v[12:13], 1, v[2:3]
	v_mov_b64_e32 v[4:5], v[220:221]
	v_mov_b64_e32 v[6:7], v[222:223]
	v_add_co_u32_e32 v8, vcc, s33, v8
	s_waitcnt vmcnt(0)
	v_lshlrev_b32_e32 v10, 16, v4
	v_addc_co_u32_e32 v9, vcc, 0, v9, vcc
	v_mul_f32_e32 v13, v1, v10
	v_mov_b64_e32 v[8:9], v[224:225]
	v_mov_b64_e32 v[10:11], v[226:227]
	v_and_b32_e32 v4, 0xffff0000, v4
	v_cvt_pk_bf16_f32 v14, v13, v129
	v_mad_u64_u32 v[12:13], s[4:5], v12, s18, v[0:1]
	v_mul_f32_e32 v4, v1, v4
	ds_write_b16 v12, v14
	v_cvt_pk_bf16_f32 v4, v4, v129
	ds_write_b16 v12, v4 offset:272
	s_waitcnt vmcnt(0)
; #define LAS __attribute__((address_space(3)))
; __device__ __forceinline__ bf16_t f2bf(float f) { return (bf16_t)(pk_bf16(f, 0.f) & 0xffffu); }
; __device__ __forceinline__ float bflo(unsigned w) { return __uint_as_float(w << 16); }
; __device__ __forceinline__ float bfhi(unsigned w) { return __uint_as_float(w & 0xffff0000u); }
; __device__ __forceinline__ void ret_kv_unit(int b, int h, int c, LAS unsigned char* lds, const bf16_t* PROJ, float* KV, int tid) {
;     ...
;     for (int r = 0; r < 4; ++r) { const int idx = tid + 512 * r, tok = idx & 127, seg = idx >> 7;
;         const bf16_t* rp = PROJ + (R0 + tok) * EIN + h * 128 + seg * 8;
;         const u32x4 kv = *(const u32x4*)(rp + 1024), vv = *(const u32x4*)(rp + 2048);
;         const float wj = exp2f(lg2 * (float)(127 - tok)) * 0.08838834764831845f;
; #pragma unroll
;         for (int i = 0; i < 4; ++i) {
;             *(LAS bf16_t*)(KT + (seg * 8 + 2 * i) * 272 + tok * 2) = f2bf(bflo(kv[i]) * wj);
;             *(LAS bf16_t*)(KT + (seg * 8 + 2 * i + 1) * 272 + tok * 2) = f2bf(bfhi(kv[i]) * wj);
;             *(LAS bf16_t*)(VT + (seg * 8 + 2 * i) * 272 + tok * 2) = (bf16_t)(vv[i] & 0xffffu);
;             *(LAS bf16_t*)(VT + (seg * 8 + 2 * i + 1) * 272 + tok * 2) = (bf16_t)(vv[i] >> 16); } }
	ds_write_b16 v12, v8 offset:34816
	ds_write_b16_d16_hi v12, v8 offset:35088
	v_lshlrev_b32_e32 v4, 16, v5
	v_mul_f32_e32 v4, v1, v4
	v_cvt_pk_bf16_f32 v4, v4, v129
	ds_write_b16 v12, v4 offset:544
	v_and_b32_e32 v4, 0xffff0000, v5
	v_mul_f32_e32 v4, v1, v4
	v_cvt_pk_bf16_f32 v4, v4, v129
	ds_write_b16 v12, v4 offset:816
	ds_write_b16 v12, v9 offset:35360
	ds_write_b16_d16_hi v12, v9 offset:35632
	v_lshlrev_b32_e32 v4, 16, v6
	v_mul_f32_e32 v4, v1, v4
	v_cvt_pk_bf16_f32 v4, v4, v129
	ds_write_b16 v12, v4 offset:1088
	v_and_b32_e32 v4, 0xffff0000, v6
	v_mul_f32_e32 v4, v1, v4
	v_cvt_pk_bf16_f32 v4, v4, v129
	ds_write_b16 v12, v4 offset:1360
	ds_write_b16 v12, v10 offset:35904
	ds_write_b16_d16_hi v12, v10 offset:36176
	v_lshlrev_b32_e32 v4, 16, v7
	v_mul_f32_e32 v4, v1, v4
	v_cvt_pk_bf16_f32 v4, v4, v129
	ds_write_b16 v12, v4 offset:1632
	v_and_b32_e32 v4, 0xffff0000, v7
	v_mul_f32_e32 v4, v1, v4
	v_cvt_pk_bf16_f32 v4, v4, v129
	ds_write_b16 v12, v4 offset:1904
	ds_write_b16 v12, v11 offset:36448
	ds_write_b16_d16_hi v12, v11 offset:36720
	v_add_u32_e32 v4, 0x400, v47
	v_ashrrev_i32_e32 v4, 4, v4
	v_and_b32_e32 v12, -8, v4
	v_ashrrev_i32_e32 v13, 31, v12
	v_lshl_add_u64 v[8:9], v[12:13], 1, v[2:3]
	v_mov_b64_e32 v[4:5], v[228:229]
	v_mov_b64_e32 v[6:7], v[230:231]
	v_add_co_u32_e32 v8, vcc, s33, v8
	s_waitcnt vmcnt(0)
	v_lshlrev_b32_e32 v10, 16, v4
	v_addc_co_u32_e32 v9, vcc, 0, v9, vcc
	v_mul_f32_e32 v13, v1, v10
	v_mov_b64_e32 v[8:9], v[232:233]
	v_mov_b64_e32 v[10:11], v[234:235]
	v_and_b32_e32 v4, 0xffff0000, v4
	v_cvt_pk_bf16_f32 v14, v13, v129
	v_mad_u64_u32 v[12:13], s[4:5], v12, s18, v[0:1]
	v_mul_f32_e32 v4, v1, v4
	ds_write_b16 v12, v14
	v_cvt_pk_bf16_f32 v4, v4, v129
	ds_write_b16 v12, v4 offset:272
	s_waitcnt vmcnt(0)
	ds_write_b16 v12, v8 offset:34816
	ds_write_b16_d16_hi v12, v8 offset:35088
	v_lshlrev_b32_e32 v4, 16, v5
	v_mul_f32_e32 v4, v1, v4
	v_cvt_pk_bf16_f32 v4, v4, v129
	ds_write_b16 v12, v4 offset:544
	v_and_b32_e32 v4, 0xffff0000, v5
	v_mul_f32_e32 v4, v1, v4
	v_cvt_pk_bf16_f32 v4, v4, v129
	ds_write_b16 v12, v4 offset:816
	ds_write_b16 v12, v9 offset:35360
	ds_write_b16_d16_hi v12, v9 offset:35632
	v_lshlrev_b32_e32 v4, 16, v6
	v_mul_f32_e32 v4, v1, v4
	v_cvt_pk_bf16_f32 v4, v4, v129
	ds_write_b16 v12, v4 offset:1088
	v_and_b32_e32 v4, 0xffff0000, v6
	v_mul_f32_e32 v4, v1, v4
	v_cvt_pk_bf16_f32 v4, v4, v129
	ds_write_b16 v12, v4 offset:1360
	ds_write_b16 v12, v10 offset:35904
	ds_write_b16_d16_hi v12, v10 offset:36176
	v_lshlrev_b32_e32 v4, 16, v7
	v_mul_f32_e32 v4, v1, v4
	v_cvt_pk_bf16_f32 v4, v4, v129
	ds_write_b16 v12, v4 offset:1632
	v_and_b32_e32 v4, 0xffff0000, v7
	v_mul_f32_e32 v4, v1, v4
	v_cvt_pk_bf16_f32 v4, v4, v129
	ds_write_b16 v12, v4 offset:1904
	ds_write_b16 v12, v11 offset:36448
	ds_write_b16_d16_hi v12, v11 offset:36720
	v_add_u32_e32 v4, 0x600, v47
	v_ashrrev_i32_e32 v4, 4, v4
	v_and_b32_e32 v10, -8, v4
	v_ashrrev_i32_e32 v11, 31, v10
	v_lshl_add_u64 v[6:7], v[10:11], 1, v[2:3]
	v_mov_b64_e32 v[2:3], v[236:237]
	v_mov_b64_e32 v[4:5], v[238:239]
	v_add_co_u32_e32 v6, vcc, s33, v6
	s_waitcnt vmcnt(0)
	v_lshlrev_b32_e32 v8, 16, v2
	v_addc_co_u32_e32 v7, vcc, 0, v7, vcc
	v_mul_f32_e32 v11, v1, v8
	v_mov_b64_e32 v[6:7], v[240:241]
	v_mov_b64_e32 v[8:9], v[242:243]
	v_cvt_pk_bf16_f32 v12, v11, v129
	v_mad_u64_u32 v[10:11], s[4:5], v10, s18, v[0:1]
	v_and_b32_e32 v0, 0xffff0000, v2
	v_mul_f32_e32 v0, v1, v0
	ds_write_b16 v10, v12
	v_cvt_pk_bf16_f32 v0, v0, v129
	ds_write_b16 v10, v0 offset:272
	s_waitcnt vmcnt(0)
	ds_write_b16 v10, v6 offset:34816
	ds_write_b16_d16_hi v10, v6 offset:35088
	v_lshlrev_b32_e32 v0, 16, v3
	v_mul_f32_e32 v0, v1, v0
	v_cvt_pk_bf16_f32 v0, v0, v129
	ds_write_b16 v10, v0 offset:544
	v_and_b32_e32 v0, 0xffff0000, v3
	v_mul_f32_e32 v0, v1, v0
	v_cvt_pk_bf16_f32 v0, v0, v129
	ds_write_b16 v10, v0 offset:816
	ds_write_b16 v10, v7 offset:35360
	ds_write_b16_d16_hi v10, v7 offset:35632
	v_lshlrev_b32_e32 v0, 16, v4
	v_mul_f32_e32 v0, v1, v0
	v_cvt_pk_bf16_f32 v0, v0, v129
	ds_write_b16 v10, v0 offset:1088
	v_and_b32_e32 v0, 0xffff0000, v4
	v_mul_f32_e32 v0, v1, v0
	v_cvt_pk_bf16_f32 v0, v0, v129
	ds_write_b16 v10, v0 offset:1360
	ds_write_b16 v10, v8 offset:35904
	ds_write_b16_d16_hi v10, v8 offset:36176
	v_lshlrev_b32_e32 v0, 16, v5
	v_mul_f32_e32 v0, v1, v0
	v_cvt_pk_bf16_f32 v0, v0, v129
	ds_write_b16 v10, v0 offset:1632
	v_and_b32_e32 v0, 0xffff0000, v5
	v_mul_f32_e32 v0, v1, v0
	v_cvt_pk_bf16_f32 v0, v0, v129
	ds_write_b16 v10, v0 offset:1904
	ds_write_b16 v10, v9 offset:36448
	ds_write_b16_d16_hi v10, v9 offset:36720
	v_ashrrev_i32_e32 v0, 2, v47
	v_bfi_b32 v18, -16, v0, v47
	v_mad_u64_u32 v[0:1], s[4:5], v18, s18, v[20:21]
	s_waitcnt lgkmcnt(0)
	s_barrier
; #define LAS __attribute__((address_space(3)))
; __device__ __forceinline__ f32x4 mfma16(bf16x8 a, bf16x8 b, f32x4 c) { return __builtin_amdgcn_mfma_f32_16x16x32_bf16(a, b, c, 0, 0, 0); }
; __device__ __forceinline__ void ret_kv_unit(int b, int h, int c, LAS unsigned char* lds, const bf16_t* PROJ, float* KV, int tid) {
;     ...
;     __syncthreads();
;     bf16x8 kf[4];
; #pragma unroll
;     for (int kk = 0; kk < 4; ++kk) kf[kk] = *(const LAS bf16x8*)(KT + (16 * wave + fr) * 272 + (32 * kk + 8 * fq) * 2);
;     float* outp = KV + ((size_t)((b * 8 + h) * 32 + c)) * 16384 + (size_t)(16 * wave + fr) * 128 + 4 * fq;
; #pragma unroll
;     for (int cb = 0; cb < 8; ++cb) { f32x4 acc = {0.f, 0.f, 0.f, 0.f};
; #pragma unroll
;         for (int kk = 0; kk < 4; ++kk) { const bf16x8 vf = *(const LAS bf16x8*)(VT + (16 * cb + fr) * 272 + (32 * kk + 8 * fq) * 2); acc = mfma16(vf, kf[kk], acc); }
;         *(f32x4*)(outp + 16 * cb) = acc; }
;     __syncthreads();
	ds_read_b128 v[12:15], v0
	ds_read_b128 v[8:11], v0 offset:64
	ds_read_b128 v[4:7], v0 offset:128
	ds_read_b128 v[0:3], v0 offset:192
	ds_read_b128 v[20:23], v17 offset:34816
	ds_read_b128 v[24:27], v17 offset:34880
	s_waitcnt lgkmcnt(1)
	v_mfma_f32_16x16x32_bf16 v[20:23], v[20:23], v[12:15], 0
	s_and_b32 s4, s38, 0x100
	s_or_b32 s1, s1, s4
	s_or_b32 s0, s1, s0
	s_waitcnt lgkmcnt(0)
	v_mfma_f32_16x16x32_bf16 v[20:23], v[24:27], v[8:11], v[20:23]
	ds_read_b128 v[24:27], v17 offset:34944
	s_lshl_b32 s0, s0, 16
	s_add_u32 s0, s3, s0
	s_waitcnt lgkmcnt(0)
	v_mfma_f32_16x16x32_bf16 v[20:23], v[24:27], v[4:7], v[20:23]
	ds_read_b128 v[24:27], v17 offset:35008
	v_ashrrev_i32_e32 v19, 31, v18
	s_addc_u32 s1, s11, 0
	s_waitcnt lgkmcnt(0)
	v_mfma_f32_16x16x32_bf16 v[20:23], v[24:27], v[0:3], v[20:23]
	v_lshlrev_b64 v[18:19], 9, v[18:19]
	v_lshl_add_u64 v[18:19], s[0:1], 0, v[18:19]
	v_lshl_add_u64 v[18:19], v[18:19], 0, v[128:129]
	s_nop 4
	global_store_dwordx4 v[18:19], v[20:23], off
	ds_read_b128 v[20:23], v17 offset:39168
	ds_read_b128 v[24:27], v17 offset:39232
	s_waitcnt lgkmcnt(1)
	v_mfma_f32_16x16x32_bf16 v[20:23], v[20:23], v[12:15], 0
	s_waitcnt lgkmcnt(0)
	v_mfma_f32_16x16x32_bf16 v[20:23], v[24:27], v[8:11], v[20:23]
	ds_read_b128 v[24:27], v17 offset:39296
	s_waitcnt lgkmcnt(0)
	v_mfma_f32_16x16x32_bf16 v[20:23], v[24:27], v[4:7], v[20:23]
	ds_read_b128 v[24:27], v17 offset:39360
	s_waitcnt lgkmcnt(0)
	v_mfma_f32_16x16x32_bf16 v[20:23], v[24:27], v[0:3], v[20:23]
	ds_read_b128 v[24:27], v17 offset:43584
	s_nop 6
	global_store_dwordx4 v[18:19], v[20:23], off offset:64
	ds_read_b128 v[20:23], v17 offset:43520
	s_waitcnt lgkmcnt(0)
	v_mfma_f32_16x16x32_bf16 v[20:23], v[20:23], v[12:15], 0
	v_mfma_f32_16x16x32_bf16 v[20:23], v[24:27], v[8:11], v[20:23]
	ds_read_b128 v[24:27], v17 offset:43648
	s_waitcnt lgkmcnt(0)
	v_mfma_f32_16x16x32_bf16 v[20:23], v[24:27], v[4:7], v[20:23]
	ds_read_b128 v[24:27], v17 offset:43712
	s_waitcnt lgkmcnt(0)
	v_mfma_f32_16x16x32_bf16 v[20:23], v[24:27], v[0:3], v[20:23]
	ds_read_b128 v[24:27], v17 offset:47936
	s_nop 6
	global_store_dwordx4 v[18:19], v[20:23], off offset:128
	ds_read_b128 v[20:23], v17 offset:47872
	s_waitcnt lgkmcnt(0)
	v_mfma_f32_16x16x32_bf16 v[20:23], v[20:23], v[12:15], 0
	v_mfma_f32_16x16x32_bf16 v[20:23], v[24:27], v[8:11], v[20:23]
	ds_read_b128 v[24:27], v17 offset:48000
	s_waitcnt lgkmcnt(0)
	v_mfma_f32_16x16x32_bf16 v[20:23], v[24:27], v[4:7], v[20:23]
	ds_read_b128 v[24:27], v17 offset:48064
	s_waitcnt lgkmcnt(0)
	v_mfma_f32_16x16x32_bf16 v[20:23], v[24:27], v[0:3], v[20:23]
	ds_read_b128 v[24:27], v17 offset:52288
	s_nop 6
	global_store_dwordx4 v[18:19], v[20:23], off offset:192
	ds_read_b128 v[20:23], v17 offset:52224
	s_waitcnt lgkmcnt(0)
	v_mfma_f32_16x16x32_bf16 v[20:23], v[20:23], v[12:15], 0
	v_mfma_f32_16x16x32_bf16 v[20:23], v[24:27], v[8:11], v[20:23]
	ds_read_b128 v[24:27], v17 offset:52352
	s_waitcnt lgkmcnt(0)
	v_mfma_f32_16x16x32_bf16 v[20:23], v[24:27], v[4:7], v[20:23]
	ds_read_b128 v[24:27], v17 offset:52416
	s_waitcnt lgkmcnt(0)
	v_mfma_f32_16x16x32_bf16 v[20:23], v[24:27], v[0:3], v[20:23]
	ds_read_b128 v[24:27], v17 offset:56640
	s_nop 6
	global_store_dwordx4 v[18:19], v[20:23], off offset:256
	ds_read_b128 v[20:23], v17 offset:56576
	s_waitcnt lgkmcnt(0)
	v_mfma_f32_16x16x32_bf16 v[20:23], v[20:23], v[12:15], 0
	v_mfma_f32_16x16x32_bf16 v[20:23], v[24:27], v[8:11], v[20:23]
	ds_read_b128 v[24:27], v17 offset:56704
	s_waitcnt lgkmcnt(0)
	v_mfma_f32_16x16x32_bf16 v[20:23], v[24:27], v[4:7], v[20:23]
	ds_read_b128 v[24:27], v17 offset:56768
	s_waitcnt lgkmcnt(0)
	v_mfma_f32_16x16x32_bf16 v[20:23], v[24:27], v[0:3], v[20:23]
	ds_read_b128 v[24:27], v17 offset:60992
	s_nop 6
	global_store_dwordx4 v[18:19], v[20:23], off offset:320
	ds_read_b128 v[20:23], v17 offset:60928
	s_waitcnt lgkmcnt(0)
	v_mfma_f32_16x16x32_bf16 v[20:23], v[20:23], v[12:15], 0
	v_mfma_f32_16x16x32_bf16 v[20:23], v[24:27], v[8:11], v[20:23]
	ds_read_b128 v[24:27], v17 offset:61056
	s_waitcnt lgkmcnt(0)
	v_mfma_f32_16x16x32_bf16 v[20:23], v[24:27], v[4:7], v[20:23]
	ds_read_b128 v[24:27], v17 offset:61120
	s_waitcnt lgkmcnt(0)
	v_mfma_f32_16x16x32_bf16 v[20:23], v[24:27], v[0:3], v[20:23]
	s_nop 7
	global_store_dwordx4 v[18:19], v[20:23], off offset:384
	ds_read_b128 v[20:23], v17 offset:65280
	s_waitcnt lgkmcnt(0)
	v_mfma_f32_16x16x32_bf16 v[12:15], v[20:23], v[12:15], 0
	ds_read_b128 v[20:23], v17 offset:65344
	s_waitcnt lgkmcnt(0)
	v_mfma_f32_16x16x32_bf16 v[8:11], v[20:23], v[8:11], v[12:15]
	s_nop 4
	ds_read_b128 v[12:15], v17 offset:65408
	s_waitcnt lgkmcnt(0)
	v_mfma_f32_16x16x32_bf16 v[4:7], v[12:15], v[4:7], v[8:11]
	s_nop 2
	ds_read_b128 v[8:11], v17 offset:65472
	s_waitcnt lgkmcnt(0)
	v_mfma_f32_16x16x32_bf16 v[0:3], v[8:11], v[0:3], v[4:7]
	s_nop 7
	global_store_dwordx4 v[18:19], v[0:3], off offset:448
	s_barrier
	s_and_b32 s0, s38, 0xffffff00
	s_cmpk_lg_i32 s0, 0x600
	s_cbranch_scc0 .LBB0_456
